# P6 gate/up GEMM epilogue: per-row statistics loaded before the last K-iteration's LDS-DMA prefetches (quarter row per lane + cross-lane sum), so the epilogue no longer waits for the next unit's prefet
# speedup vs baseline: 1.2424x; 1.0127x over previous
.LBB0_1610:
	ds_read_b128 v[130:133], v190
	ds_read_b128 v[134:137], v190 offset:1024
	ds_read_b128 v[138:141], v190 offset:2048
	ds_read_b128 v[142:145], v190 offset:3072
	ds_read_b128 v[146:149], v191
	ds_read_b128 v[150:153], v191 offset:1024
	ds_read_b128 v[154:157], v191 offset:2048
	ds_read_b128 v[158:161], v191 offset:3072
	s_add_u32 s26, s24, 0xfffc0080
	s_addc_u32 s27, s25, -1
	s_cmp_eq_u32 s52, 12
	s_cselect_b32 s29, s19, s27
	s_cselect_b32 s28, s48, s26
	s_cselect_b32 s27, s17, s51
	s_cselect_b32 s26, s49, s50
	v_lshl_add_u64 v[186:187], s[24:25], 0, v[170:171]
	s_add_i32 m0, s36, 0xc000
	ds_read_b128 v[178:181], v192
	ds_read_b128 v[182:185], v192 offset:1024
	ds_read_b128 v[196:199], v192 offset:2048
	ds_read_b128 v[200:203], v192 offset:3072
	ds_read_b128 v[204:207], v192 offset:4096
	ds_read_b128 v[208:211], v192 offset:5120
	ds_read_b128 v[212:215], v192 offset:6144
	ds_read_b128 v[216:219], v192 offset:7168
	global_load_lds_dwordx4 v[186:187], off
	v_lshl_add_u64 v[186:187], s[24:25], 0, v[172:173]
	s_add_i32 m0, s36, 0xe000
	s_nop 0
	global_load_lds_dwordx4 v[186:187], off
	s_waitcnt vmcnt(8)
	s_waitcnt lgkmcnt(0)
	s_barrier
	s_setprio 1
	s_waitcnt lgkmcnt(0)
	v_mfma_f32_16x16x32_bf16 v[126:129], v[130:133], v[178:181], v[126:129]
	v_mfma_f32_16x16x32_bf16 v[122:125], v[138:141], v[178:181], v[122:125]
	v_mfma_f32_16x16x32_bf16 v[110:113], v[130:133], v[196:199], v[110:113]
	v_mfma_f32_16x16x32_bf16 v[106:109], v[138:141], v[196:199], v[106:109]
	v_mfma_f32_16x16x32_bf16 v[94:97], v[130:133], v[204:207], v[94:97]
	v_mfma_f32_16x16x32_bf16 v[90:93], v[138:141], v[204:207], v[90:93]
	v_mfma_f32_16x16x32_bf16 v[78:81], v[130:133], v[212:215], v[78:81]
	v_mfma_f32_16x16x32_bf16 v[74:77], v[138:141], v[212:215], v[74:77]
	v_mfma_f32_16x16x32_bf16 v[126:129], v[134:137], v[182:185], v[126:129]
	v_mfma_f32_16x16x32_bf16 v[122:125], v[142:145], v[182:185], v[122:125]
	v_mfma_f32_16x16x32_bf16 v[110:113], v[134:137], v[200:203], v[110:113]
	v_mfma_f32_16x16x32_bf16 v[106:109], v[142:145], v[200:203], v[106:109]
	v_mfma_f32_16x16x32_bf16 v[94:97], v[134:137], v[208:211], v[94:97]
	v_mfma_f32_16x16x32_bf16 v[90:93], v[142:145], v[208:211], v[90:93]
	v_mfma_f32_16x16x32_bf16 v[78:81], v[134:137], v[216:219], v[78:81]
	v_mfma_f32_16x16x32_bf16 v[74:77], v[142:145], v[216:219], v[74:77]
	s_setprio 0
	s_setprio 1
	v_mfma_f32_16x16x32_bf16 v[118:121], v[146:149], v[178:181], v[118:121]
	v_mfma_f32_16x16x32_bf16 v[114:117], v[154:157], v[178:181], v[114:117]
	v_mfma_f32_16x16x32_bf16 v[102:105], v[146:149], v[196:199], v[102:105]
	v_mfma_f32_16x16x32_bf16 v[98:101], v[154:157], v[196:199], v[98:101]
	v_mfma_f32_16x16x32_bf16 v[86:89], v[146:149], v[204:207], v[86:89]
	v_mfma_f32_16x16x32_bf16 v[82:85], v[154:157], v[204:207], v[82:85]
	v_mfma_f32_16x16x32_bf16 v[70:73], v[146:149], v[212:215], v[70:73]
	v_mfma_f32_16x16x32_bf16 v[66:69], v[154:157], v[212:215], v[66:69]
	v_mfma_f32_16x16x32_bf16 v[118:121], v[150:153], v[182:185], v[118:121]
	v_mfma_f32_16x16x32_bf16 v[114:117], v[158:161], v[182:185], v[114:117]
	v_mfma_f32_16x16x32_bf16 v[102:105], v[150:153], v[200:203], v[102:105]
	v_mfma_f32_16x16x32_bf16 v[98:101], v[158:161], v[200:203], v[98:101]
	v_mfma_f32_16x16x32_bf16 v[86:89], v[150:153], v[208:211], v[86:89]
	v_mfma_f32_16x16x32_bf16 v[82:85], v[158:161], v[208:211], v[82:85]
	v_mfma_f32_16x16x32_bf16 v[70:73], v[150:153], v[216:219], v[70:73]
	v_mfma_f32_16x16x32_bf16 v[66:69], v[158:161], v[216:219], v[66:69]
	s_setprio 0
	s_barrier
	s_add_i32 s53, s44, s33
	v_lshl_add_u64 v[186:187], s[26:27], 0, v[166:167]
	s_mov_b32 m0, s53
	ds_read_b128 v[178:181], v192 offset:16384
	ds_read_b128 v[182:185], v192 offset:17408
	ds_read_b128 v[196:199], v192 offset:18432
	ds_read_b128 v[200:203], v192 offset:19456
	ds_read_b128 v[204:207], v192 offset:20480
	ds_read_b128 v[208:211], v192 offset:21504
	ds_read_b128 v[212:215], v192 offset:22528
	ds_read_b128 v[216:219], v192 offset:23552
	global_load_lds_dwordx4 v[186:187], off
	s_add_i32 m0, s53, 0x2000
	s_add_u32 s54, s26, 0x40000
	v_lshl_add_u64 v[220:221], s[26:27], 0, v[162:163]
	s_addc_u32 s55, s27, 0
	s_add_i32 s53, s45, s33
	global_load_lds_dwordx4 v[220:221], off
	v_lshl_add_u64 v[222:223], s[54:55], 0, v[166:167]
	s_mov_b32 m0, s53
	v_lshl_add_u64 v[224:225], s[28:29], 0, v[164:165]
	global_load_lds_dwordx4 v[222:223], off
	v_lshl_add_u64 v[222:223], s[54:55], 0, v[162:163]
	s_add_i32 m0, s53, 0x2000
	s_nop 0
	global_load_lds_dwordx4 v[222:223], off
	v_lshl_add_u64 v[222:223], s[28:29], 0, v[168:169]
	s_mov_b32 m0, s36
	s_nop 0
	global_load_lds_dwordx4 v[222:223], off
	s_mov_b32 m0, s37
	s_nop 0
	global_load_lds_dwordx4 v[224:225], off
	s_waitcnt vmcnt(8)
	s_waitcnt lgkmcnt(0)
	s_barrier
	s_setprio 1
	s_waitcnt lgkmcnt(0)
	v_mfma_f32_16x16x32_bf16 v[62:65], v[130:133], v[178:181], v[62:65]
	v_mfma_f32_16x16x32_bf16 v[58:61], v[138:141], v[178:181], v[58:61]
	v_mfma_f32_16x16x32_bf16 v[46:49], v[130:133], v[196:199], v[46:49]
	v_mfma_f32_16x16x32_bf16 v[42:45], v[138:141], v[196:199], v[42:45]
	v_mfma_f32_16x16x32_bf16 v[30:33], v[130:133], v[204:207], v[30:33]
	v_mfma_f32_16x16x32_bf16 v[26:29], v[138:141], v[204:207], v[26:29]
	v_mfma_f32_16x16x32_bf16 v[14:17], v[130:133], v[212:215], v[14:17]
	v_mfma_f32_16x16x32_bf16 v[10:13], v[138:141], v[212:215], v[10:13]
	v_mfma_f32_16x16x32_bf16 v[62:65], v[134:137], v[182:185], v[62:65]
	v_mfma_f32_16x16x32_bf16 v[58:61], v[142:145], v[182:185], v[58:61]
	v_mfma_f32_16x16x32_bf16 v[46:49], v[134:137], v[200:203], v[46:49]
	v_mfma_f32_16x16x32_bf16 v[42:45], v[142:145], v[200:203], v[42:45]
	v_mfma_f32_16x16x32_bf16 v[30:33], v[134:137], v[208:211], v[30:33]
	v_mfma_f32_16x16x32_bf16 v[26:29], v[142:145], v[208:211], v[26:29]
	v_mfma_f32_16x16x32_bf16 v[14:17], v[134:137], v[216:219], v[14:17]
	v_mfma_f32_16x16x32_bf16 v[10:13], v[142:145], v[216:219], v[10:13]
	s_setprio 0
	s_setprio 1
	v_mfma_f32_16x16x32_bf16 v[54:57], v[146:149], v[178:181], v[54:57]
	v_mfma_f32_16x16x32_bf16 v[50:53], v[154:157], v[178:181], v[50:53]
	v_mfma_f32_16x16x32_bf16 v[38:41], v[146:149], v[196:199], v[38:41]
	v_mfma_f32_16x16x32_bf16 v[34:37], v[154:157], v[196:199], v[34:37]
	v_mfma_f32_16x16x32_bf16 v[22:25], v[146:149], v[204:207], v[22:25]
	v_mfma_f32_16x16x32_bf16 v[18:21], v[154:157], v[204:207], v[18:21]
	v_mfma_f32_16x16x32_bf16 v[6:9], v[146:149], v[212:215], v[6:9]
	v_mfma_f32_16x16x32_bf16 v[2:5], v[154:157], v[212:215], v[2:5]
	v_mfma_f32_16x16x32_bf16 v[54:57], v[150:153], v[182:185], v[54:57]
	v_mfma_f32_16x16x32_bf16 v[50:53], v[158:161], v[182:185], v[50:53]
	v_mfma_f32_16x16x32_bf16 v[38:41], v[150:153], v[200:203], v[38:41]
	v_mfma_f32_16x16x32_bf16 v[34:37], v[158:161], v[200:203], v[34:37]
	v_mfma_f32_16x16x32_bf16 v[22:25], v[150:153], v[208:211], v[22:25]
	v_mfma_f32_16x16x32_bf16 v[18:21], v[158:161], v[208:211], v[18:21]
	v_mfma_f32_16x16x32_bf16 v[6:9], v[150:153], v[216:219], v[6:9]
	v_mfma_f32_16x16x32_bf16 v[2:5], v[158:161], v[216:219], v[2:5]
	s_setprio 0
	s_barrier
	s_cmp_lg_u32 s52, 12
	s_cbranch_scc1 .Lgu_skip_ld
	v_lshl_add_u32 v254, s6, 8, v1
	v_and_b32_e32 v255, 48, v0
	v_lshl_add_u32 v254, v254, 6, v255
	v_add_u32_e32 v255, 0x2000, v254
	global_load_dwordx4 v[228:231], v254, s[10:11]
	global_load_dwordx4 v[232:235], v254, s[10:11] offset:1024
	global_load_dwordx4 v[236:239], v254, s[10:11] offset:2048
	global_load_dwordx4 v[240:243], v254, s[10:11] offset:3072
	global_load_dwordx4 v[246:249], v255, s[10:11]
	global_load_dwordx4 v[250:253], v255, s[10:11] offset:1024
.Lgu_skip_ld:
	s_add_i32 s53, 0, 0x18000
	s_add_i32 s54, 0, 0x1c000
	v_add_u32_e32 v142, s53, v188
	v_add_u32_e32 v158, s54, v188
	ds_read_b128 v[130:133], v142
	ds_read_b128 v[134:137], v142 offset:1024
	ds_read_b128 v[138:141], v142 offset:2048
	ds_read_b128 v[142:145], v142 offset:3072
	ds_read_b128 v[146:149], v158
	ds_read_b128 v[150:153], v158 offset:1024
	ds_read_b128 v[154:157], v158 offset:2048
	ds_read_b128 v[158:161], v158 offset:3072
	s_add_u32 s28, s28, 0x40000
	s_addc_u32 s29, s29, 0
	s_mov_b32 m0, s38
	v_lshl_add_u64 v[226:227], s[28:29], 0, v[168:169]
	ds_read_b128 v[178:181], v192 offset:32768
	ds_read_b128 v[182:185], v192 offset:33792
	ds_read_b128 v[196:199], v192 offset:34816
	ds_read_b128 v[200:203], v192 offset:35840
	ds_read_b128 v[204:207], v192 offset:36864
	ds_read_b128 v[208:211], v192 offset:37888
	ds_read_b128 v[212:215], v192 offset:38912
	ds_read_b128 v[216:219], v192 offset:39936
	global_load_lds_dwordx4 v[226:227], off
	v_lshl_add_u64 v[226:227], s[28:29], 0, v[164:165]
	s_mov_b32 m0, s39
	s_nop 0
	global_load_lds_dwordx4 v[226:227], off
	s_cmp_eq_u32 s52, 12
	s_cbranch_scc1 .Lgu_w1_last
	s_waitcnt vmcnt(8)
	s_branch .Lgu_w1_end
.Lgu_w1_last:
	s_waitcnt vmcnt(14)
.Lgu_w1_end:
	s_waitcnt lgkmcnt(0)
	s_barrier
	s_setprio 1
	s_waitcnt lgkmcnt(0)
	v_mfma_f32_16x16x32_bf16 v[126:129], v[130:133], v[178:181], v[126:129]
	v_mfma_f32_16x16x32_bf16 v[122:125], v[138:141], v[178:181], v[122:125]
	v_mfma_f32_16x16x32_bf16 v[110:113], v[130:133], v[196:199], v[110:113]
	v_mfma_f32_16x16x32_bf16 v[106:109], v[138:141], v[196:199], v[106:109]
	v_mfma_f32_16x16x32_bf16 v[94:97], v[130:133], v[204:207], v[94:97]
	v_mfma_f32_16x16x32_bf16 v[90:93], v[138:141], v[204:207], v[90:93]
	v_mfma_f32_16x16x32_bf16 v[78:81], v[130:133], v[212:215], v[78:81]
	v_mfma_f32_16x16x32_bf16 v[74:77], v[138:141], v[212:215], v[74:77]
	v_mfma_f32_16x16x32_bf16 v[126:129], v[134:137], v[182:185], v[126:129]
	v_mfma_f32_16x16x32_bf16 v[122:125], v[142:145], v[182:185], v[122:125]
	v_mfma_f32_16x16x32_bf16 v[110:113], v[134:137], v[200:203], v[110:113]
	v_mfma_f32_16x16x32_bf16 v[106:109], v[142:145], v[200:203], v[106:109]
	v_mfma_f32_16x16x32_bf16 v[94:97], v[134:137], v[208:211], v[94:97]
	v_mfma_f32_16x16x32_bf16 v[90:93], v[142:145], v[208:211], v[90:93]
	v_mfma_f32_16x16x32_bf16 v[78:81], v[134:137], v[216:219], v[78:81]
	v_mfma_f32_16x16x32_bf16 v[74:77], v[142:145], v[216:219], v[74:77]
	s_setprio 0
	s_setprio 1
	v_mfma_f32_16x16x32_bf16 v[118:121], v[146:149], v[178:181], v[118:121]
	v_mfma_f32_16x16x32_bf16 v[114:117], v[154:157], v[178:181], v[114:117]
	v_mfma_f32_16x16x32_bf16 v[102:105], v[146:149], v[196:199], v[102:105]
	v_mfma_f32_16x16x32_bf16 v[98:101], v[154:157], v[196:199], v[98:101]
	v_mfma_f32_16x16x32_bf16 v[86:89], v[146:149], v[204:207], v[86:89]
	v_mfma_f32_16x16x32_bf16 v[82:85], v[154:157], v[204:207], v[82:85]
	v_mfma_f32_16x16x32_bf16 v[70:73], v[146:149], v[212:215], v[70:73]
	v_mfma_f32_16x16x32_bf16 v[66:69], v[154:157], v[212:215], v[66:69]
	v_mfma_f32_16x16x32_bf16 v[118:121], v[150:153], v[182:185], v[118:121]
	v_mfma_f32_16x16x32_bf16 v[114:117], v[158:161], v[182:185], v[114:117]
	v_mfma_f32_16x16x32_bf16 v[102:105], v[150:153], v[200:203], v[102:105]
	v_mfma_f32_16x16x32_bf16 v[98:101], v[158:161], v[200:203], v[98:101]
	v_mfma_f32_16x16x32_bf16 v[86:89], v[150:153], v[208:211], v[86:89]
	v_mfma_f32_16x16x32_bf16 v[82:85], v[158:161], v[208:211], v[82:85]
	v_mfma_f32_16x16x32_bf16 v[70:73], v[150:153], v[216:219], v[70:73]
	v_mfma_f32_16x16x32_bf16 v[66:69], v[158:161], v[216:219], v[66:69]
	s_setprio 0
	s_barrier
	s_add_i32 s28, s53, s33
	v_lshl_add_u64 v[186:187], v[186:187], 0, s[12:13]
	s_mov_b32 m0, s28
	ds_read_b128 v[178:181], v192 offset:49152
	ds_read_b128 v[182:185], v192 offset:50176
	ds_read_b128 v[196:199], v192 offset:51200
	ds_read_b128 v[200:203], v192 offset:52224
	ds_read_b128 v[204:207], v192 offset:53248
	ds_read_b128 v[208:211], v192 offset:54272
	ds_read_b128 v[212:215], v192 offset:55296
	ds_read_b128 v[216:219], v192 offset:56320
	global_load_lds_dwordx4 v[186:187], off
	s_add_i32 m0, s28, 0x2000
	s_add_u32 s26, s26, 0x40080
	v_lshl_add_u64 v[186:187], v[220:221], 0, s[12:13]
	s_addc_u32 s27, s27, 0
	s_add_i32 s28, s54, s33
	global_load_lds_dwordx4 v[186:187], off
	v_lshl_add_u64 v[186:187], s[26:27], 0, v[166:167]
	s_mov_b32 m0, s28
	s_nop 0
	global_load_lds_dwordx4 v[186:187], off
	v_lshl_add_u64 v[186:187], s[26:27], 0, v[162:163]
	s_add_i32 m0, s28, 0x2000
	s_nop 0
	global_load_lds_dwordx4 v[186:187], off
	v_lshl_add_u64 v[186:187], v[222:223], 0, s[12:13]
	s_mov_b32 m0, s41
	s_nop 0
	global_load_lds_dwordx4 v[186:187], off
	v_lshl_add_u64 v[186:187], v[224:225], 0, s[12:13]
	s_mov_b32 m0, s42
	s_nop 0
	global_load_lds_dwordx4 v[186:187], off
	s_cmp_eq_u32 s52, 12
	s_cbranch_scc1 .Lgu_w2_last
	s_waitcnt vmcnt(8)
	s_branch .Lgu_w2_end

.Lgu_w2_end:
	s_waitcnt lgkmcnt(0)
	s_barrier
	s_setprio 1
	s_waitcnt lgkmcnt(0)
	v_mfma_f32_16x16x32_bf16 v[62:65], v[130:133], v[178:181], v[62:65]
	v_mfma_f32_16x16x32_bf16 v[58:61], v[138:141], v[178:181], v[58:61]
	v_mfma_f32_16x16x32_bf16 v[46:49], v[130:133], v[196:199], v[46:49]
	v_mfma_f32_16x16x32_bf16 v[42:45], v[138:141], v[196:199], v[42:45]
	v_mfma_f32_16x16x32_bf16 v[30:33], v[130:133], v[204:207], v[30:33]
	v_mfma_f32_16x16x32_bf16 v[26:29], v[138:141], v[204:207], v[26:29]
	v_mfma_f32_16x16x32_bf16 v[14:17], v[130:133], v[212:215], v[14:17]
	v_mfma_f32_16x16x32_bf16 v[10:13], v[138:141], v[212:215], v[10:13]
	v_mfma_f32_16x16x32_bf16 v[62:65], v[134:137], v[182:185], v[62:65]
	v_mfma_f32_16x16x32_bf16 v[58:61], v[142:145], v[182:185], v[58:61]
	v_mfma_f32_16x16x32_bf16 v[46:49], v[134:137], v[200:203], v[46:49]
	v_mfma_f32_16x16x32_bf16 v[42:45], v[142:145], v[200:203], v[42:45]
	v_mfma_f32_16x16x32_bf16 v[30:33], v[134:137], v[208:211], v[30:33]
	v_mfma_f32_16x16x32_bf16 v[26:29], v[142:145], v[208:211], v[26:29]
	v_mfma_f32_16x16x32_bf16 v[14:17], v[134:137], v[216:219], v[14:17]
	v_mfma_f32_16x16x32_bf16 v[10:13], v[142:145], v[216:219], v[10:13]
	s_setprio 0
	s_setprio 1
	v_mfma_f32_16x16x32_bf16 v[54:57], v[146:149], v[178:181], v[54:57]
	v_mfma_f32_16x16x32_bf16 v[50:53], v[154:157], v[178:181], v[50:53]
	v_mfma_f32_16x16x32_bf16 v[38:41], v[146:149], v[196:199], v[38:41]
	v_mfma_f32_16x16x32_bf16 v[34:37], v[154:157], v[196:199], v[34:37]
	v_mfma_f32_16x16x32_bf16 v[22:25], v[146:149], v[204:207], v[22:25]
	v_mfma_f32_16x16x32_bf16 v[18:21], v[154:157], v[204:207], v[18:21]
	v_mfma_f32_16x16x32_bf16 v[6:9], v[146:149], v[212:215], v[6:9]
	v_mfma_f32_16x16x32_bf16 v[2:5], v[154:157], v[212:215], v[2:5]
	v_mfma_f32_16x16x32_bf16 v[54:57], v[150:153], v[182:185], v[54:57]
	v_mfma_f32_16x16x32_bf16 v[50:53], v[158:161], v[182:185], v[50:53]
	v_mfma_f32_16x16x32_bf16 v[38:41], v[150:153], v[200:203], v[38:41]
	v_mfma_f32_16x16x32_bf16 v[34:37], v[158:161], v[200:203], v[34:37]
	v_mfma_f32_16x16x32_bf16 v[22:25], v[150:153], v[208:211], v[22:25]
	v_mfma_f32_16x16x32_bf16 v[18:21], v[158:161], v[208:211], v[18:21]
	v_mfma_f32_16x16x32_bf16 v[6:9], v[150:153], v[216:219], v[6:9]
	v_mfma_f32_16x16x32_bf16 v[2:5], v[158:161], v[216:219], v[2:5]
	s_setprio 0
	s_barrier
	s_add_i32 s52, s52, 2
	s_add_u32 s24, s24, 0x100
	s_addc_u32 s25, s25, 0
	s_add_u32 s50, s50, 0x100
	s_addc_u32 s51, s51, 0
	s_cmp_gt_u32 s52, 13
	s_cbranch_scc0 .LBB0_1610
	s_and_b64 vcc, exec, s[14:15]
	s_cbranch_vccz .LBB0_1613
	s_barrier
.LBB0_1613:
	v_and_b32_e32 v130, 63, v0
	v_lshlrev_b32_e32 v130, 2, v130
	v_xor_b32_e32 v131, 0x80, v130
	v_xor_b32_e32 v130, 64, v130
	s_waitcnt vmcnt(8)
	v_add_f32_e32 v228, v228, v229
	v_add_f32_e32 v230, v230, v231
	v_add_f32_e32 v232, v232, v233
	v_add_f32_e32 v234, v234, v235
	v_add_f32_e32 v236, v236, v237
	v_add_f32_e32 v238, v238, v239
	v_add_f32_e32 v240, v240, v241
	v_add_f32_e32 v242, v242, v243
	v_add_f32_e32 v246, v246, v247
	v_add_f32_e32 v248, v248, v249
	v_add_f32_e32 v250, v250, v251
	v_add_f32_e32 v252, v252, v253
	v_add_f32_e32 v228, v228, v230
	v_add_f32_e32 v232, v232, v234
	v_add_f32_e32 v236, v236, v238
	v_add_f32_e32 v240, v240, v242
	v_add_f32_e32 v246, v246, v248
	v_add_f32_e32 v250, v250, v252
	ds_bpermute_b32 v229, v130, v228
	ds_bpermute_b32 v233, v130, v232
	ds_bpermute_b32 v237, v130, v236
	ds_bpermute_b32 v241, v130, v240
	ds_bpermute_b32 v247, v130, v246
	ds_bpermute_b32 v251, v130, v250
	s_waitcnt lgkmcnt(0)
	v_add_f32_e32 v228, v228, v229
	v_add_f32_e32 v232, v232, v233
	v_add_f32_e32 v236, v236, v237
	v_add_f32_e32 v240, v240, v241
	v_add_f32_e32 v246, v246, v247
	v_add_f32_e32 v250, v250, v251
	ds_bpermute_b32 v229, v131, v228
	ds_bpermute_b32 v233, v131, v232
	ds_bpermute_b32 v237, v131, v236
	ds_bpermute_b32 v241, v131, v240
	ds_bpermute_b32 v247, v131, v246
	ds_bpermute_b32 v251, v131, v250
	s_waitcnt lgkmcnt(0)
	v_add_f32_e32 v228, v228, v229
	v_add_f32_e32 v232, v232, v233
	v_add_f32_e32 v236, v236, v237
	v_add_f32_e32 v240, v240, v241
	v_add_f32_e32 v246, v246, v247
	v_add_f32_e32 v250, v250, v251
	v_fmamk_f32 v228, v228, 0x3a800000, v193
	v_fmamk_f32 v232, v232, 0x3a800000, v193
	v_fmamk_f32 v236, v236, 0x3a800000, v193
	v_fmamk_f32 v240, v240, 0x3a800000, v193
	v_fmamk_f32 v246, v246, 0x3a800000, v193
	v_fmamk_f32 v250, v250, 0x3a800000, v193
	v_rsq_f32_e32 v229, v228
	v_rsq_f32_e32 v233, v232
	v_rsq_f32_e32 v237, v236
	v_rsq_f32_e32 v241, v240
	v_rsq_f32_e32 v247, v246
	v_rsq_f32_e32 v251, v250
	s_nop 0
	v_mul_f32_e32 v230, v228, v229
	v_mul_f32_e32 v234, v232, v233
	v_mul_f32_e32 v238, v236, v237
	v_mul_f32_e32 v242, v240, v241
	v_mul_f32_e32 v248, v246, v247
	v_mul_f32_e32 v252, v250, v251
	v_fma_f32 v230, -v230, v229, 1.0
	v_fma_f32 v234, -v234, v233, 1.0
	v_fma_f32 v238, -v238, v237, 1.0
	v_fma_f32 v242, -v242, v241, 1.0
	v_fma_f32 v248, -v248, v247, 1.0
	v_fma_f32 v252, -v252, v251, 1.0
	v_mul_f32_e32 v231, 0.5, v229
	v_mul_f32_e32 v235, 0.5, v233
	v_mul_f32_e32 v239, 0.5, v237
	v_mul_f32_e32 v243, 0.5, v241
	v_mul_f32_e32 v249, 0.5, v247
	v_mul_f32_e32 v253, 0.5, v251
	v_fma_f32 v228, v231, v230, v229
	v_fma_f32 v229, v235, v234, v233
	v_fma_f32 v230, v239, v238, v237
	v_fma_f32 v231, v243, v242, v241
	v_fma_f32 v232, v249, v248, v247
	v_fma_f32 v233, v253, v252, v251
	global_load_dwordx4 v[234:237], v255, s[10:11] offset:2048
	global_load_dwordx4 v[238:241], v255, s[10:11] offset:3072
	v_mov_b32_e32 v242, v130
	v_mov_b32_e32 v243, v131
	v_lshl_add_u32 v178, s6, 8, v1
	v_ashrrev_i32_e32 v179, 31, v178
	s_nop 0
	v_or_b32_e32 v184, 16, v178
	v_or_b32_e32 v182, 32, v178
	v_or_b32_e32 v180, 48, v178
	v_ashrrev_i32_e32 v185, 31, v184
	v_ashrrev_i32_e32 v183, 31, v182
	v_ashrrev_i32_e32 v181, 31, v180
	s_nop 0
	v_lshl_or_b32 v186, s7, 7, v189
	v_ashrrev_i32_e32 v187, 31, v186
	s_nop 0
	s_nop 0
	s_nop 1
	s_nop 0
	s_nop 0
	s_nop 1
	s_nop 1
	s_nop 1
	v_mov_b32_e32 v212, v228
	v_pk_mul_f32 v[126:127], v[126:127], v[212:213] op_sel_hi:[1,0]
	v_pk_mul_f32 v[122:123], v[122:123], v[212:213] op_sel_hi:[1,0]
	v_pk_mul_f32 v[128:129], v[128:129], v[212:213] op_sel_hi:[1,0]
	v_pk_mul_f32 v[118:119], v[118:119], v[212:213] op_sel_hi:[1,0]
	v_pk_mul_f32 v[114:115], v[114:115], v[212:213] op_sel_hi:[1,0]
	v_pk_mul_f32 v[120:121], v[120:121], v[212:213] op_sel_hi:[1,0]
	v_pk_mul_f32 v[124:125], v[124:125], v[212:213] op_sel_hi:[1,0]
	v_mul_f32_e32 v179, 0xbfb8aa3b, v126
	v_mul_f32_e32 v181, 0xbfb8aa3b, v127
	v_mul_f32_e32 v183, 0xbfb8aa3b, v122
	v_mul_f32_e32 v185, 0xbfb8aa3b, v123
	v_mul_f32_e32 v195, 0xbfb8aa3b, v128
	v_mul_f32_e32 v213, 0xbfb8aa3b, v129
	v_mul_f32_e32 v214, 0xbfb8aa3b, v124
	v_mul_f32_e32 v215, 0xbfb8aa3b, v125
	v_exp_f32_e32 v179, v179
	v_exp_f32_e32 v181, v181
	v_exp_f32_e32 v183, v183
	v_exp_f32_e32 v185, v185
	v_exp_f32_e32 v195, v195
	v_exp_f32_e32 v213, v213
	v_exp_f32_e32 v214, v214
	v_exp_f32_e32 v215, v215
	v_add_f32_e32 v179, 1.0, v179
	v_add_f32_e32 v181, 1.0, v181
	v_add_f32_e32 v183, 1.0, v183
	v_add_f32_e32 v185, 1.0, v185
	v_add_f32_e32 v195, 1.0, v195
	v_add_f32_e32 v213, 1.0, v213
	v_add_f32_e32 v220, 1.0, v214
	v_add_f32_e32 v221, 1.0, v215
	v_rcp_f32_e32 v214, v179
	v_rcp_f32_e32 v215, v181
	v_rcp_f32_e32 v216, v183
	v_rcp_f32_e32 v217, v185
	v_rcp_f32_e32 v218, v195
	v_rcp_f32_e32 v219, v213
	v_rcp_f32_e32 v220, v220
	v_rcp_f32_e32 v221, v221
	v_pk_mul_f32 v[126:127], v[126:127], v[214:215]
	v_pk_mul_f32 v[122:123], v[122:123], v[216:217]
	v_pk_mul_f32 v[128:129], v[128:129], v[218:219]
	v_pk_mul_f32 v[118:119], v[118:119], v[126:127]
	v_pk_mul_f32 v[114:115], v[114:115], v[122:123]
	v_pk_mul_f32 v[120:121], v[120:121], v[128:129]
	v_pk_mul_f32 v[122:123], v[124:125], v[220:221]
	v_pk_mul_f32 v[116:117], v[116:117], v[212:213] op_sel_hi:[1,0]
	v_cvt_pk_bf16_f32 v118, v118, v119
	v_pk_mul_f32 v[116:117], v[116:117], v[122:123]
	v_cvt_pk_bf16_f32 v119, v120, v121
	s_nop 0
	s_nop 0
	s_nop 0
	s_nop 1
	v_cvt_pk_bf16_f32 v121, v116, v117
	v_cvt_pk_bf16_f32 v120, v114, v115
	v_mov_b64_e32 v[114:115], s[68:69]
	s_nop 0
	s_nop 1
	s_nop 1
	v_mad_i64_i32 v[122:123], s[6:7], v178, s47, v[114:115]
	v_lshlrev_b64 v[116:117], 1, v[186:187]
	v_mov_b32_e32 v124, v229
	v_pk_mul_f32 v[110:111], v[110:111], v[124:125] op_sel_hi:[1,0]
	v_lshl_add_u64 v[122:123], v[122:123], 0, v[116:117]
	v_mul_f32_e32 v125, 0xbfb8aa3b, v110
	v_mul_f32_e32 v126, 0xbfb8aa3b, v111
	v_exp_f32_e32 v125, v125
	v_exp_f32_e32 v126, v126
	global_store_dwordx4 v[122:123], v[118:121], off
	v_pk_mul_f32 v[106:107], v[106:107], v[124:125] op_sel_hi:[1,0]
	s_nop 0
	v_add_f32_e32 v118, 1.0, v125
	v_add_f32_e32 v119, 1.0, v126
	v_rcp_f32_e32 v118, v118
	v_mul_f32_e32 v120, 0xbfb8aa3b, v106
	v_mul_f32_e32 v121, 0xbfb8aa3b, v107
	v_rcp_f32_e32 v119, v119
	v_exp_f32_e32 v120, v120
	v_exp_f32_e32 v121, v121
	v_pk_mul_f32 v[102:103], v[102:103], v[124:125] op_sel_hi:[1,0]
	v_pk_mul_f32 v[110:111], v[110:111], v[118:119]
	v_add_f32_e32 v120, 1.0, v120
	v_add_f32_e32 v121, 1.0, v121
	v_pk_mul_f32 v[102:103], v[102:103], v[110:111]
	v_pk_mul_f32 v[110:111], v[112:113], v[124:125] op_sel_hi:[1,0]
	v_rcp_f32_e32 v120, v120
	v_rcp_f32_e32 v121, v121
	v_mul_f32_e32 v112, 0xbfb8aa3b, v110
	v_mul_f32_e32 v113, 0xbfb8aa3b, v111
	v_exp_f32_e32 v112, v112
	v_exp_f32_e32 v113, v113
	v_pk_mul_f32 v[106:107], v[106:107], v[120:121]
	v_pk_mul_f32 v[98:99], v[98:99], v[124:125] op_sel_hi:[1,0]
	v_pk_mul_f32 v[108:109], v[108:109], v[124:125] op_sel_hi:[1,0]
	v_pk_mul_f32 v[106:107], v[98:99], v[106:107]
	v_add_f32_e32 v98, 1.0, v112
	v_add_f32_e32 v99, 1.0, v113
	v_mul_f32_e32 v112, 0xbfb8aa3b, v108
	v_mul_f32_e32 v113, 0xbfb8aa3b, v109
	v_exp_f32_e32 v112, v112
	v_exp_f32_e32 v113, v113
	v_rcp_f32_e32 v98, v98
	v_rcp_f32_e32 v99, v99
	v_add_f32_e32 v112, 1.0, v112
	v_add_f32_e32 v113, 1.0, v113
	v_rcp_f32_e32 v112, v112
	v_rcp_f32_e32 v113, v113
	v_pk_mul_f32 v[98:99], v[110:111], v[98:99]
	v_pk_mul_f32 v[104:105], v[104:105], v[124:125] op_sel_hi:[1,0]
	v_pk_mul_f32 v[100:101], v[100:101], v[124:125] op_sel_hi:[1,0]
	v_pk_mul_f32 v[104:105], v[104:105], v[98:99]
	v_pk_mul_f32 v[98:99], v[108:109], v[112:113]
	v_pk_mul_f32 v[108:109], v[100:101], v[98:99]
	v_cvt_pk_bf16_f32 v98, v102, v103
	s_nop 0
	s_nop 0
	s_nop 0
	v_cvt_pk_bf16_f32 v101, v108, v109
	s_nop 0
	v_cvt_pk_bf16_f32 v99, v104, v105
	v_cvt_pk_bf16_f32 v100, v106, v107
	s_nop 0
	s_nop 1
	s_nop 1
	v_mad_i64_i32 v[102:103], s[6:7], v184, s47, v[114:115]
	v_lshl_add_u64 v[102:103], v[102:103], 0, v[116:117]
	v_mov_b32_e32 v104, v230
	v_pk_mul_f32 v[94:95], v[94:95], v[104:105] op_sel_hi:[1,0]
	global_store_dwordx4 v[102:103], v[98:101], off
	v_mul_f32_e32 v105, 0xbfb8aa3b, v94
	v_mul_f32_e32 v106, 0xbfb8aa3b, v95
	v_exp_f32_e32 v105, v105
	v_exp_f32_e32 v106, v106
	v_add_u32_e32 v102, 0x90, v178
	v_ashrrev_i32_e32 v103, 31, v102
	v_add_f32_e32 v98, 1.0, v105
	v_add_f32_e32 v99, 1.0, v106
	v_pk_mul_f32 v[90:91], v[90:91], v[104:105] op_sel_hi:[1,0]
	v_rcp_f32_e32 v98, v98
	v_mul_f32_e32 v100, 0xbfb8aa3b, v90
	v_mul_f32_e32 v101, 0xbfb8aa3b, v91
	v_rcp_f32_e32 v99, v99
	v_exp_f32_e32 v100, v100
	v_exp_f32_e32 v101, v101
	v_pk_mul_f32 v[86:87], v[86:87], v[104:105] op_sel_hi:[1,0]
	v_pk_mul_f32 v[94:95], v[94:95], v[98:99]
	v_add_f32_e32 v100, 1.0, v100
	v_add_f32_e32 v101, 1.0, v101
	v_pk_mul_f32 v[86:87], v[86:87], v[94:95]
	v_pk_mul_f32 v[94:95], v[96:97], v[104:105] op_sel_hi:[1,0]
	v_rcp_f32_e32 v100, v100
	v_rcp_f32_e32 v101, v101
	v_mul_f32_e32 v96, 0xbfb8aa3b, v94
	v_mul_f32_e32 v97, 0xbfb8aa3b, v95
	v_exp_f32_e32 v96, v96
	v_exp_f32_e32 v97, v97
	v_pk_mul_f32 v[90:91], v[90:91], v[100:101]
	v_pk_mul_f32 v[82:83], v[82:83], v[104:105] op_sel_hi:[1,0]
	v_pk_mul_f32 v[92:93], v[92:93], v[104:105] op_sel_hi:[1,0]
	v_pk_mul_f32 v[90:91], v[82:83], v[90:91]
	v_add_f32_e32 v82, 1.0, v96
	v_add_f32_e32 v83, 1.0, v97
	v_mul_f32_e32 v96, 0xbfb8aa3b, v92
	v_mul_f32_e32 v97, 0xbfb8aa3b, v93
	v_exp_f32_e32 v96, v96
	v_exp_f32_e32 v97, v97
	v_rcp_f32_e32 v82, v82
	v_rcp_f32_e32 v83, v83
	v_add_f32_e32 v96, 1.0, v96
	v_add_f32_e32 v97, 1.0, v97
	v_rcp_f32_e32 v96, v96
	v_rcp_f32_e32 v97, v97
	v_pk_mul_f32 v[82:83], v[94:95], v[82:83]
	v_pk_mul_f32 v[88:89], v[88:89], v[104:105] op_sel_hi:[1,0]
	v_pk_mul_f32 v[84:85], v[84:85], v[104:105] op_sel_hi:[1,0]
	v_pk_mul_f32 v[88:89], v[88:89], v[82:83]
	v_pk_mul_f32 v[82:83], v[92:93], v[96:97]
	v_pk_mul_f32 v[92:93], v[84:85], v[82:83]
	v_cvt_pk_bf16_f32 v82, v86, v87
	v_add_u32_e32 v104, 0x80, v178
	v_ashrrev_i32_e32 v105, 31, v104
	v_add_u32_e32 v100, 0xa0, v178
	v_cvt_pk_bf16_f32 v85, v92, v93
	v_ashrrev_i32_e32 v101, 31, v100
	v_cvt_pk_bf16_f32 v83, v88, v89
	v_cvt_pk_bf16_f32 v84, v90, v91
	s_nop 0
	s_nop 1
	s_nop 1
	v_mad_i64_i32 v[86:87], s[6:7], v182, s47, v[114:115]
	v_lshl_add_u64 v[86:87], v[86:87], 0, v[116:117]
	v_mov_b32_e32 v88, v231
	v_pk_mul_f32 v[78:79], v[78:79], v[88:89] op_sel_hi:[1,0]
	global_store_dwordx4 v[86:87], v[82:85], off
	v_mul_f32_e32 v89, 0xbfb8aa3b, v78
	v_mul_f32_e32 v90, 0xbfb8aa3b, v79
	v_exp_f32_e32 v89, v89
	v_exp_f32_e32 v90, v90
	v_add_f32_e32 v82, 1.0, v89
	v_add_f32_e32 v83, 1.0, v90
	v_pk_mul_f32 v[74:75], v[74:75], v[88:89] op_sel_hi:[1,0]
	v_rcp_f32_e32 v82, v82
	v_mul_f32_e32 v84, 0xbfb8aa3b, v74
	v_mul_f32_e32 v85, 0xbfb8aa3b, v75
	v_rcp_f32_e32 v83, v83
	v_exp_f32_e32 v84, v84
	v_exp_f32_e32 v85, v85
	v_pk_mul_f32 v[70:71], v[70:71], v[88:89] op_sel_hi:[1,0]
	v_pk_mul_f32 v[78:79], v[78:79], v[82:83]
	v_add_f32_e32 v84, 1.0, v84
	v_add_f32_e32 v85, 1.0, v85
	v_pk_mul_f32 v[70:71], v[70:71], v[78:79]
	v_pk_mul_f32 v[78:79], v[80:81], v[88:89] op_sel_hi:[1,0]
	v_rcp_f32_e32 v84, v84
	v_rcp_f32_e32 v85, v85
	v_mul_f32_e32 v80, 0xbfb8aa3b, v78
	v_mul_f32_e32 v81, 0xbfb8aa3b, v79
	v_exp_f32_e32 v80, v80
	v_exp_f32_e32 v81, v81
	v_pk_mul_f32 v[74:75], v[74:75], v[84:85]
	v_pk_mul_f32 v[66:67], v[66:67], v[88:89] op_sel_hi:[1,0]
	v_pk_mul_f32 v[76:77], v[76:77], v[88:89] op_sel_hi:[1,0]
	v_pk_mul_f32 v[74:75], v[66:67], v[74:75]
	v_add_f32_e32 v66, 1.0, v80
	v_add_f32_e32 v67, 1.0, v81
	v_mul_f32_e32 v80, 0xbfb8aa3b, v76
	v_mul_f32_e32 v81, 0xbfb8aa3b, v77
	v_exp_f32_e32 v80, v80
	v_exp_f32_e32 v81, v81
	v_rcp_f32_e32 v66, v66
	v_rcp_f32_e32 v67, v67
	v_add_f32_e32 v80, 1.0, v80
	v_add_f32_e32 v81, 1.0, v81
	v_rcp_f32_e32 v80, v80
	v_rcp_f32_e32 v81, v81
	v_pk_mul_f32 v[66:67], v[78:79], v[66:67]
	v_pk_mul_f32 v[72:73], v[72:73], v[88:89] op_sel_hi:[1,0]
	v_pk_mul_f32 v[68:69], v[68:69], v[88:89] op_sel_hi:[1,0]
	v_pk_mul_f32 v[72:73], v[72:73], v[66:67]
	v_pk_mul_f32 v[66:67], v[76:77], v[80:81]
	v_pk_mul_f32 v[76:77], v[68:69], v[66:67]
	v_cvt_pk_bf16_f32 v66, v70, v71
	v_mad_i64_i32 v[70:71], s[6:7], v180, s47, v[114:115]
	v_cvt_pk_bf16_f32 v67, v72, v73
	v_cvt_pk_bf16_f32 v68, v74, v75
	v_cvt_pk_bf16_f32 v69, v76, v77
	v_lshl_add_u64 v[70:71], v[70:71], 0, v[116:117]
	global_store_dwordx4 v[70:71], v[66:69], off
	s_nop 0
	s_nop 0
	s_nop 0
	s_nop 0
	v_add_u32_e32 v98, 0xb0, v178
	v_ashrrev_i32_e32 v99, 31, v98
	s_nop 0
	s_nop 1
	s_nop 0
	s_nop 1
	s_nop 1
	v_mov_b32_e32 v126, v232
	v_pk_mul_f32 v[62:63], v[62:63], v[126:127] op_sel_hi:[1,0]
	v_pk_mul_f32 v[58:59], v[58:59], v[126:127] op_sel_hi:[1,0]
	v_mul_f32_e32 v74, 0xbfb8aa3b, v62
	v_exp_f32_e32 v99, v74
	v_mul_f32_e32 v74, 0xbfb8aa3b, v63
	v_exp_f32_e32 v101, v74
	v_mul_f32_e32 v103, 0xbfb8aa3b, v59
	v_add_f32_e32 v99, 1.0, v99
	v_rcp_f32_e32 v128, v99
	v_add_f32_e32 v99, 1.0, v101
	v_mul_f32_e32 v101, 0xbfb8aa3b, v58
	v_exp_f32_e32 v101, v101
	v_rcp_f32_e32 v129, v99
	v_exp_f32_e32 v103, v103
	v_pk_mul_f32 v[54:55], v[54:55], v[126:127] op_sel_hi:[1,0]
	v_add_f32_e32 v99, 1.0, v101
	v_pk_mul_f32 v[62:63], v[62:63], v[128:129]
	v_rcp_f32_e32 v130, v99
	v_add_f32_e32 v99, 1.0, v103
	v_pk_mul_f32 v[54:55], v[54:55], v[62:63]
	v_pk_mul_f32 v[62:63], v[64:65], v[126:127] op_sel_hi:[1,0]
	v_rcp_f32_e32 v131, v99
	v_mul_f32_e32 v64, 0xbfb8aa3b, v62
	v_mul_f32_e32 v65, 0xbfb8aa3b, v63
	v_exp_f32_e32 v64, v64
	v_exp_f32_e32 v65, v65
	v_pk_mul_f32 v[58:59], v[58:59], v[130:131]
	v_pk_mul_f32 v[50:51], v[50:51], v[126:127] op_sel_hi:[1,0]
	v_pk_mul_f32 v[60:61], v[60:61], v[126:127] op_sel_hi:[1,0]
	v_pk_mul_f32 v[58:59], v[50:51], v[58:59]
	v_add_f32_e32 v50, 1.0, v64
	v_add_f32_e32 v51, 1.0, v65
	v_mul_f32_e32 v64, 0xbfb8aa3b, v60
	v_mul_f32_e32 v65, 0xbfb8aa3b, v61
	v_exp_f32_e32 v64, v64
	v_exp_f32_e32 v65, v65
	v_rcp_f32_e32 v50, v50
	v_rcp_f32_e32 v51, v51
	v_add_f32_e32 v64, 1.0, v64
	v_add_f32_e32 v65, 1.0, v65
	v_rcp_f32_e32 v64, v64
	v_rcp_f32_e32 v65, v65
	v_pk_mul_f32 v[50:51], v[62:63], v[50:51]
	v_pk_mul_f32 v[56:57], v[56:57], v[126:127] op_sel_hi:[1,0]
	v_pk_mul_f32 v[52:53], v[52:53], v[126:127] op_sel_hi:[1,0]
	v_pk_mul_f32 v[56:57], v[56:57], v[50:51]
	v_pk_mul_f32 v[50:51], v[60:61], v[64:65]
	v_pk_mul_f32 v[60:61], v[52:53], v[50:51]
	v_cvt_pk_bf16_f32 v50, v54, v55
	s_nop 0
	s_nop 0
	s_nop 0
	v_cvt_pk_bf16_f32 v53, v60, v61
	s_nop 0
	v_cvt_pk_bf16_f32 v51, v56, v57
	v_cvt_pk_bf16_f32 v52, v58, v59
	s_nop 0
	s_nop 1
	s_nop 1
	v_mad_i64_i32 v[54:55], s[6:7], v104, s47, v[114:115]
	v_lshl_add_u64 v[54:55], v[54:55], 0, v[116:117]
	v_mov_b32_e32 v56, v233
	v_pk_mul_f32 v[46:47], v[46:47], v[56:57] op_sel_hi:[1,0]
	global_store_dwordx4 v[54:55], v[50:53], off
	v_mul_f32_e32 v57, 0xbfb8aa3b, v46
	v_mul_f32_e32 v58, 0xbfb8aa3b, v47
	v_exp_f32_e32 v57, v57
	v_exp_f32_e32 v58, v58
	v_add_f32_e32 v50, 1.0, v57
	v_add_f32_e32 v51, 1.0, v58
	v_pk_mul_f32 v[42:43], v[42:43], v[56:57] op_sel_hi:[1,0]
	v_rcp_f32_e32 v50, v50
	v_mul_f32_e32 v52, 0xbfb8aa3b, v42
	v_mul_f32_e32 v53, 0xbfb8aa3b, v43
	v_rcp_f32_e32 v51, v51
	v_exp_f32_e32 v52, v52
	v_exp_f32_e32 v53, v53
	v_pk_mul_f32 v[38:39], v[38:39], v[56:57] op_sel_hi:[1,0]
	v_pk_mul_f32 v[46:47], v[46:47], v[50:51]
	v_add_f32_e32 v52, 1.0, v52
	v_add_f32_e32 v53, 1.0, v53
	v_pk_mul_f32 v[38:39], v[38:39], v[46:47]
	v_pk_mul_f32 v[46:47], v[48:49], v[56:57] op_sel_hi:[1,0]
	v_rcp_f32_e32 v52, v52
	v_rcp_f32_e32 v53, v53
	v_mul_f32_e32 v48, 0xbfb8aa3b, v46
	v_mul_f32_e32 v49, 0xbfb8aa3b, v47
	v_exp_f32_e32 v48, v48
	v_exp_f32_e32 v49, v49
	v_pk_mul_f32 v[42:43], v[42:43], v[52:53]
	v_pk_mul_f32 v[34:35], v[34:35], v[56:57] op_sel_hi:[1,0]
	v_pk_mul_f32 v[44:45], v[44:45], v[56:57] op_sel_hi:[1,0]
	v_pk_mul_f32 v[42:43], v[34:35], v[42:43]
	v_add_f32_e32 v34, 1.0, v48
	v_add_f32_e32 v35, 1.0, v49
	v_mul_f32_e32 v48, 0xbfb8aa3b, v44
	v_mul_f32_e32 v49, 0xbfb8aa3b, v45
	v_exp_f32_e32 v48, v48
	v_exp_f32_e32 v49, v49
	v_rcp_f32_e32 v34, v34
	v_rcp_f32_e32 v35, v35
	v_add_f32_e32 v48, 1.0, v48
	v_add_f32_e32 v49, 1.0, v49
	v_rcp_f32_e32 v48, v48
	v_rcp_f32_e32 v49, v49
	v_pk_mul_f32 v[34:35], v[46:47], v[34:35]
	v_pk_mul_f32 v[40:41], v[40:41], v[56:57] op_sel_hi:[1,0]
	v_pk_mul_f32 v[36:37], v[36:37], v[56:57] op_sel_hi:[1,0]
	v_pk_mul_f32 v[40:41], v[40:41], v[34:35]
	v_pk_mul_f32 v[34:35], v[44:45], v[48:49]
	v_pk_mul_f32 v[44:45], v[36:37], v[34:35]
	v_cvt_pk_bf16_f32 v34, v38, v39
	s_nop 0
	s_nop 0
	s_nop 0
	v_cvt_pk_bf16_f32 v37, v44, v45
	s_nop 0
	v_cvt_pk_bf16_f32 v35, v40, v41
	v_cvt_pk_bf16_f32 v36, v42, v43
	s_nop 0
	s_nop 1
	s_nop 1
	v_mad_i64_i32 v[38:39], s[6:7], v102, s47, v[114:115]
	v_lshl_add_u64 v[38:39], v[38:39], 0, v[116:117]
	s_waitcnt vmcnt(5)
	v_add_f32_e32 v234, v234, v235
	v_add_f32_e32 v236, v236, v237
	v_add_f32_e32 v238, v238, v239
	v_add_f32_e32 v240, v240, v241
	v_add_f32_e32 v234, v234, v236
	v_add_f32_e32 v238, v238, v240
	ds_bpermute_b32 v235, v242, v234
	ds_bpermute_b32 v239, v242, v238
	s_waitcnt lgkmcnt(0)
	v_add_f32_e32 v234, v234, v235
	v_add_f32_e32 v238, v238, v239
	ds_bpermute_b32 v235, v243, v234
	ds_bpermute_b32 v239, v243, v238
	s_waitcnt lgkmcnt(0)
	v_add_f32_e32 v234, v234, v235
	v_add_f32_e32 v238, v238, v239
	v_fmamk_f32 v234, v234, 0x3a800000, v193
	v_fmamk_f32 v238, v238, 0x3a800000, v193
	v_rsq_f32_e32 v235, v234
	v_rsq_f32_e32 v239, v238
	s_nop 0
	v_mul_f32_e32 v236, v234, v235
	v_mul_f32_e32 v240, v238, v239
	v_fma_f32 v236, -v236, v235, 1.0
	v_fma_f32 v240, -v240, v239, 1.0
	v_mul_f32_e32 v237, 0.5, v235
	v_mul_f32_e32 v241, 0.5, v239
	v_fma_f32 v246, v237, v236, v235
	v_fma_f32 v247, v241, v240, v239
	v_mov_b32_e32 v40, v246
	v_pk_mul_f32 v[30:31], v[30:31], v[40:41] op_sel_hi:[1,0]
	global_store_dwordx4 v[38:39], v[34:37], off
	v_mul_f32_e32 v41, 0xbfb8aa3b, v30
	v_mul_f32_e32 v42, 0xbfb8aa3b, v31
	v_exp_f32_e32 v41, v41
	v_exp_f32_e32 v42, v42
	v_add_f32_e32 v34, 1.0, v41
	v_add_f32_e32 v35, 1.0, v42
	v_pk_mul_f32 v[26:27], v[26:27], v[40:41] op_sel_hi:[1,0]
	v_rcp_f32_e32 v34, v34
	v_mul_f32_e32 v36, 0xbfb8aa3b, v26
	v_mul_f32_e32 v37, 0xbfb8aa3b, v27
	v_rcp_f32_e32 v35, v35
	v_exp_f32_e32 v36, v36
	v_exp_f32_e32 v37, v37
	v_pk_mul_f32 v[22:23], v[22:23], v[40:41] op_sel_hi:[1,0]
	v_pk_mul_f32 v[30:31], v[30:31], v[34:35]
	v_add_f32_e32 v36, 1.0, v36
	v_add_f32_e32 v37, 1.0, v37
	v_pk_mul_f32 v[22:23], v[22:23], v[30:31]
	v_pk_mul_f32 v[30:31], v[32:33], v[40:41] op_sel_hi:[1,0]
	v_rcp_f32_e32 v36, v36
	v_rcp_f32_e32 v37, v37
	v_mul_f32_e32 v32, 0xbfb8aa3b, v30
	v_mul_f32_e32 v33, 0xbfb8aa3b, v31
	v_exp_f32_e32 v32, v32
	v_exp_f32_e32 v33, v33
	v_pk_mul_f32 v[26:27], v[26:27], v[36:37]
	v_pk_mul_f32 v[18:19], v[18:19], v[40:41] op_sel_hi:[1,0]
	v_pk_mul_f32 v[28:29], v[28:29], v[40:41] op_sel_hi:[1,0]
	v_pk_mul_f32 v[26:27], v[18:19], v[26:27]
	v_add_f32_e32 v18, 1.0, v32
	v_add_f32_e32 v19, 1.0, v33
	v_mul_f32_e32 v32, 0xbfb8aa3b, v28
	v_mul_f32_e32 v33, 0xbfb8aa3b, v29
	v_exp_f32_e32 v32, v32
	v_exp_f32_e32 v33, v33
	v_rcp_f32_e32 v18, v18
	v_rcp_f32_e32 v19, v19
	v_add_f32_e32 v32, 1.0, v32
	v_add_f32_e32 v33, 1.0, v33
	v_rcp_f32_e32 v32, v32
	v_rcp_f32_e32 v33, v33
	v_pk_mul_f32 v[18:19], v[30:31], v[18:19]
	v_pk_mul_f32 v[24:25], v[24:25], v[40:41] op_sel_hi:[1,0]
	v_pk_mul_f32 v[20:21], v[20:21], v[40:41] op_sel_hi:[1,0]
	v_pk_mul_f32 v[24:25], v[24:25], v[18:19]
	v_pk_mul_f32 v[18:19], v[28:29], v[32:33]
	v_pk_mul_f32 v[28:29], v[20:21], v[18:19]
	v_cvt_pk_bf16_f32 v18, v22, v23
	s_nop 0
	s_nop 0
	s_nop 0
	v_cvt_pk_bf16_f32 v21, v28, v29
	s_nop 0
	v_cvt_pk_bf16_f32 v19, v24, v25
	v_cvt_pk_bf16_f32 v20, v26, v27
	s_nop 0
	s_nop 1
	s_nop 1
	v_mad_i64_i32 v[22:23], s[6:7], v100, s47, v[114:115]
	v_lshl_add_u64 v[22:23], v[22:23], 0, v[116:117]
	v_mov_b32_e32 v24, v247
	v_pk_mul_f32 v[14:15], v[14:15], v[24:25] op_sel_hi:[1,0]
	global_store_dwordx4 v[22:23], v[18:21], off
	v_mul_f32_e32 v25, 0xbfb8aa3b, v14
	v_mul_f32_e32 v26, 0xbfb8aa3b, v15
	v_exp_f32_e32 v25, v25
	v_exp_f32_e32 v26, v26
	s_andn2_b64 vcc, exec, s[4:5]
	s_mov_b64 s[4:5], -1
	v_add_f32_e32 v18, 1.0, v25
	v_add_f32_e32 v19, 1.0, v26
	v_pk_mul_f32 v[10:11], v[10:11], v[24:25] op_sel_hi:[1,0]
	v_rcp_f32_e32 v18, v18
	v_mul_f32_e32 v20, 0xbfb8aa3b, v10
	v_mul_f32_e32 v21, 0xbfb8aa3b, v11
	v_rcp_f32_e32 v19, v19
	v_exp_f32_e32 v20, v20
	v_exp_f32_e32 v21, v21
	v_pk_mul_f32 v[6:7], v[6:7], v[24:25] op_sel_hi:[1,0]
	v_pk_mul_f32 v[14:15], v[14:15], v[18:19]
	v_add_f32_e32 v20, 1.0, v20
	v_add_f32_e32 v21, 1.0, v21
	v_pk_mul_f32 v[6:7], v[6:7], v[14:15]
	v_pk_mul_f32 v[14:15], v[16:17], v[24:25] op_sel_hi:[1,0]
	v_rcp_f32_e32 v20, v20
	v_rcp_f32_e32 v21, v21
	v_mul_f32_e32 v16, 0xbfb8aa3b, v14
	v_mul_f32_e32 v17, 0xbfb8aa3b, v15
	v_exp_f32_e32 v16, v16
	v_exp_f32_e32 v17, v17
	v_pk_mul_f32 v[10:11], v[10:11], v[20:21]
	v_pk_mul_f32 v[2:3], v[2:3], v[24:25] op_sel_hi:[1,0]
	v_pk_mul_f32 v[12:13], v[12:13], v[24:25] op_sel_hi:[1,0]
	v_pk_mul_f32 v[10:11], v[2:3], v[10:11]
	v_add_f32_e32 v2, 1.0, v16
	v_add_f32_e32 v3, 1.0, v17
	v_mul_f32_e32 v16, 0xbfb8aa3b, v12
	v_mul_f32_e32 v17, 0xbfb8aa3b, v13
	v_exp_f32_e32 v16, v16
	v_exp_f32_e32 v17, v17
	v_rcp_f32_e32 v2, v2
	v_rcp_f32_e32 v3, v3
	v_add_f32_e32 v16, 1.0, v16
	v_add_f32_e32 v17, 1.0, v17
	v_rcp_f32_e32 v16, v16
	v_rcp_f32_e32 v17, v17
	v_pk_mul_f32 v[2:3], v[14:15], v[2:3]
	v_pk_mul_f32 v[8:9], v[8:9], v[24:25] op_sel_hi:[1,0]
	v_pk_mul_f32 v[4:5], v[4:5], v[24:25] op_sel_hi:[1,0]
	v_pk_mul_f32 v[8:9], v[8:9], v[2:3]
	v_pk_mul_f32 v[2:3], v[12:13], v[16:17]
	s_nop 0
	v_pk_mul_f32 v[12:13], v[4:5], v[2:3]
	v_cvt_pk_bf16_f32 v2, v6, v7
	v_mad_i64_i32 v[6:7], s[6:7], v98, s47, v[114:115]
	v_cvt_pk_bf16_f32 v3, v8, v9
	v_cvt_pk_bf16_f32 v4, v10, v11
	v_cvt_pk_bf16_f32 v5, v12, v13
	v_lshl_add_u64 v[6:7], v[6:7], 0, v[116:117]
	global_store_dwordx4 v[6:7], v[2:5], off
	s_cbranch_vccnz .LBB0_1606
	s_andn2_b64 vcc, exec, s[8:9]
	s_cbranch_vccnz .LBB0_1605
	s_barrier
	s_branch .LBB0_1605
